# baseline (speedup 1.0000x reference)
; __device__ __forceinline__ float dot4(f32x4 a, f32x4 b) { return (a.x * b.x + a.y * b.y) + (a.z * b.z + a.w * b.w); }
; __device__ __forceinline__ void group_norm_rows(const float* Y, const float* RW, const LayerP& L, bf16* dst, int gw, int NGW, int lane) {
;     ...
;             const float* yr = Y + (size_t)m * D + gi * GW;
;             f32x4 a = ((const f32x4*)yr)[lane], b = ((const f32x4*)yr)[64 + lane];
;             if (gi == 2) {
;                 const int ca = 4 * lane, cb = 256 + 4 * lane;
;                 const float ma = row16_sum((a.x + a.y) + (a.z + a.w)) * (1.f / 64.f), mb = row16_sum((b.x + b.y) + (b.z + b.w)) * (1.f / 64.f);
;                 const f32x4 da = a - ma, db = b - mb;
;                 const float ra = rsqrtf(row16_sum(dot4(da, da)) * (1.f / 64.f) + 64e-5f), rb = rsqrtf(row16_sum(dot4(db, db)) * (1.f / 64.f) + 64e-5f);
;                 const f32x4 ga = *(const f32x4*)(L.rw_lng + ca), gb = *(const f32x4*)(L.rw_lng + cb), ba = *(const f32x4*)(L.rw_lnb + ca), bb = *(const f32x4*)(L.rw_lnb + cb);
;                 const f32x4 bna = *(const f32x4*)(RW + 7 * RWSZ + (size_t)m * GW + ca), bnb = *(const f32x4*)(RW + 7 * RWSZ + (size_t)m * GW + cb);
;                 const f32x4 gga = *(const f32x4*)(RW + 6 * RWSZ + (size_t)m * GW + ca), ggb = *(const f32x4*)(RW + 6 * RWSZ + (size_t)m * GW + cb);
;                 a = (da * ra * ga + ba + bna) * gga; b = (db * rb * gb + bb + bnb) * ggb;
;             }
;             const float ss = wave_sum(dot4(a, a) + dot4(b, b));
;             const float rstd = rsqrtf(ss * (1.f / GW) + 1e-6f);
;             const f32x4 na = ((const f32x4*)(L.out_norm + gi * GW))[lane], nb = ((const f32x4*)(L.out_norm + gi * GW))[64 + lane];
.LBB0_66:
	v_readlane_b32 s0, v254, 29
	s_cmp_gt_i32 s0, 7
	s_mov_b64 s[0:1], -1
	s_cbranch_scc0 .LBB0_91
	v_readlane_b32 s0, v254, 38
	s_cmp_lg_u32 s0, 0x100
	s_cbranch_scc1 .Lp8_main
	v_readlane_b32 s0, v254, 44
	s_cmp_lt_u32 s0, 4
	s_cbranch_scc1 .Lp8_main
	v_readlane_b32 s1, v254, 39
	s_sub_i32 s0, s0, 4
	s_lshl_b32 s1, s1, 2
	s_add_i32 s30, s1, s0
	s_barrier
	s_barrier
	s_mov_b32 s28, 2
	s_waitcnt vmcnt(0) lgkmcnt(0)
	v_readlane_b32 s8, v254, 32
	v_readlane_b32 s9, v254, 33
	v_readlane_b32 s10, v254, 30
	s_nop 0
	s_load_dwordx2 s[4:5], s[8:9], 0x140
	s_load_dwordx4 s[20:23], s[8:9], 0xf8
	s_ashr_i32 s11, s10, 31
	v_lshlrev_b32_e32 v0, 4, v188
	v_add_u32_e32 v1, 0x1000, v0
	v_lshlrev_b32_e32 v2, 3, v188
	s_lshl_b64 s[0:1], s[10:11], 13
	s_lshl_b64 s[6:7], s[10:11], 11
	s_waitcnt lgkmcnt(0)
	s_add_u32 s4, s4, s0
	s_addc_u32 s5, s5, s1
	s_add_u32 s20, s20, s6
	s_addc_u32 s21, s21, s7
	s_add_u32 s22, s22, s6
	s_addc_u32 s23, s23, s7
	global_load_dwordx4 v[80:83], v0, s[4:5] offset:0
	global_load_dwordx4 v[84:87], v0, s[4:5] offset:1024
	global_load_dwordx4 v[88:91], v0, s[4:5] offset:2048
	global_load_dwordx4 v[92:95], v0, s[4:5] offset:3072
	global_load_dwordx4 v[96:99], v1, s[4:5] offset:0
	global_load_dwordx4 v[100:103], v1, s[4:5] offset:1024
	global_load_dwordx4 v[104:107], v1, s[4:5] offset:2048
	global_load_dwordx4 v[108:111], v1, s[4:5] offset:3072
	global_load_dwordx4 v[112:115], v0, s[20:21]
	global_load_dwordx4 v[116:119], v0, s[20:21] offset:1024
	global_load_dwordx4 v[120:123], v0, s[22:23]
	global_load_dwordx4 v[124:127], v0, s[22:23] offset:1024
